# per-XCD start stagger (x*2.5us) of the mlp-out GEMM phase so that its memory-bound residual epilogues do not coincide across XCDs, on top of v91
# baseline (speedup 1.0000x reference)
.LBB0_947:
	s_cmp_le_i32 s70, s3
	s_cselect_b64 s[24:25], -1, 0
	s_cmp_lt_i32 s3, s71
	s_cselect_b64 s[28:29], -1, 0
	s_and_b64 s[24:25], s[24:25], s[28:29]
	s_andn2_b64 vcc, exec, s[24:25]
	s_cbranch_vccnz .LBB0_171
	s_getreg_b32 s98, hwreg(HW_REG_XCC_ID, 0, 4)
	s_and_b32 s98, s98, 7
	s_mul_i32 s98, s98, 5
.Ldly_g4:
	s_cmp_eq_u32 s98, 0
	s_cbranch_scc1 .Ldly_g4_done
	s_sleep 16
	s_sub_u32 s98, s98, 1
	s_branch .Ldly_g4
.Ldly_g4_done:
	v_mov_b32_e32 v0, v201
	s_mov_b64 s[24:25], s[66:67]
	v_mov_b32_e32 v12, v201
	s_and_b64 vcc, exec, s[38:39]
	v_readfirstlane_b32 s38, v12
	s_cbranch_vccnz .LBB0_1016
	v_lshlrev_b32_e32 v1, 4, v12
	v_add_u32_e32 v0, 0x2000, v1
	v_ashrrev_i32_e32 v3, 31, v0
	v_lshrrev_b32_e32 v3, 22, v3
	v_add_u32_e32 v3, v0, v3
	v_ashrrev_i32_e32 v13, 10, v3
	v_mul_i32_i24_e32 v3, 0x400, v13
	v_sub_u32_e32 v0, v0, v3
	v_lshrrev_b32_e32 v3, 4, v0
	v_bitop3_b32 v0, v3, v0, 32 bitop3:0x6c
	v_ashrrev_i32_e32 v3, 31, v0
	v_lshrrev_b32_e32 v3, 26, v3
	v_add_u32_e32 v3, v0, v3
	v_ashrrev_i32_e32 v14, 6, v3
	v_and_b32_e32 v3, 0xc0, v3
	s_load_dwordx4 s[44:47], s[24:25], 0x80
	v_sub_u32_e32 v0, v0, v3
	v_bfe_i32 v3, v12, 27, 1
	v_lshrrev_b32_e32 v3, 22, v3
	v_lshlrev_b32_e32 v4, 3, v13
	v_add_u32_e32 v3, v1, v3
	v_and_b32_e32 v4, 0x7fff0, v4
	s_waitcnt lgkmcnt(0)
	v_lshlrev_b32_e32 v5, 5, v13
	v_and_b32_e32 v3, 0xfffffc00, v3
	v_add_u32_e32 v4, v14, v4
	v_and_b32_e32 v15, 32, v5
	v_ashrrev_i16_sdwa v0, v203, sext(v0) dst_sel:DWORD dst_unused:UNUSED_PAD src0_sel:DWORD src1_sel:BYTE_0
	v_sub_u32_e32 v1, v1, v3
	s_add_u32 s3, s46, 0x7000000
	v_lshl_or_b32 v4, v4, 12, v15
	v_bfe_i32 v16, v0, 0, 16
	v_lshrrev_b32_e32 v3, 4, v1
	s_mul_i32 s24, s90, 0x1700000
	s_addc_u32 s26, s47, 0
	v_add_lshl_u32 v0, v4, v16, 1
	v_bitop3_b32 v1, v3, v1, 32 bitop3:0x6c
	v_ashrrev_i32_e32 v4, 31, v12
	s_add_u32 s24, s46, s24
	v_ashrrev_i32_e32 v3, 31, v1
	v_lshrrev_b32_e32 v4, 26, v4
	s_addc_u32 s25, s47, 0
	v_lshrrev_b32_e32 v3, 26, v3
	v_add_u32_e32 v4, v12, v4
	s_add_u32 s64, s24, 0x1100000
	v_add_u32_e32 v3, v1, v3
	v_ashrrev_i32_e32 v18, 6, v4
	s_addc_u32 s65, s25, 0
	s_ashr_i32 s40, s38, 6
	v_ashrrev_i32_e32 v17, 6, v3
	v_lshlrev_b32_e32 v4, 3, v18
	v_and_b32_e32 v3, 0xc0, v3
	s_ashr_i32 s39, s38, 8
	s_lshl_b32 s66, s40, 10
	v_and_b32_e32 v4, 0x7fff0, v4
	v_lshlrev_b32_e32 v5, 5, v18
	v_sub_u32_e32 v1, v1, v3
	v_readlane_b32 s24, v255, 15
	v_add_u32_e32 v4, v17, v4
	v_and_b32_e32 v19, 32, v5
	v_ashrrev_i16_sdwa v1, v203, sext(v1) dst_sel:DWORD dst_unused:UNUSED_PAD src0_sel:DWORD src1_sel:BYTE_0
	v_readlane_b32 s25, v255, 16
	s_add_u32 s24, s64, s24
	v_lshl_or_b32 v4, v4, 12, v19
	v_bfe_i32 v20, v1, 0, 16
	s_addc_u32 s25, s65, s25
	s_add_i32 s67, s66, 0
	v_add_lshl_u32 v132, v4, v20, 1
	s_add_i32 m0, s67, 0x10000
	v_mov_b32_e32 v133, v2
	global_load_lds_dwordx4 v132, s[24:25]
	s_add_i32 m0, s67, 0x12000
	s_add_u32 s28, s24, 0x100000
	global_load_lds_dwordx4 v0, s[24:25]
	s_addc_u32 s29, s25, 0
	s_add_i32 m0, s67, 0x14000
	v_mov_b32_e32 v1, v2
	global_load_lds_dwordx4 v132, s[28:29]
	s_add_i32 m0, s67, 0x16000
	v_lshl_add_u64 v[10:11], s[24:25], 0, v[132:133]
	global_load_lds_dwordx4 v0, s[28:29]
	v_readlane_b32 s28, v255, 36
	v_readlane_b32 s29, v255, 37
	s_add_u32 s28, s3, s28
	s_addc_u32 s29, s26, s29
	s_add_i32 s68, s67, 0x2000
	s_mov_b32 m0, s67
	s_add_u32 s42, s28, 0x100000
	global_load_lds_dwordx4 v132, s[28:29]
	s_mov_b32 m0, s68
	s_addc_u32 s43, s29, 0
	s_add_i32 s69, s67, 0x4000
	global_load_lds_dwordx4 v0, s[28:29]
	s_mov_b32 m0, s69
	s_add_i32 s70, s67, 0x6000
	global_load_lds_dwordx4 v132, s[42:43]
	s_mov_b32 m0, s70
	s_cmp_eq_u32 s39, 1
	global_load_lds_dwordx4 v0, s[42:43]
	v_lshl_add_u64 v[8:9], s[24:25], 0, v[0:1]
	v_lshl_add_u64 v[4:5], s[28:29], 0, v[132:133]
	s_cselect_b64 s[42:43], -1, 0
	s_cmp_lg_u32 s39, 1
	v_lshl_add_u64 v[6:7], s[28:29], 0, v[0:1]
	s_cbranch_scc1 .LBB0_951
	s_barrier
